# sample-GEMM tile to work-group renumbering: each XCD owns a compact 4x8 tile block (fewer distinct operand blocks per L2)
# speedup vs baseline: 1.0071x; 1.0011x over previous
.LBB0_85:
	s_or_b64 exec, exec, s[2:3]
	s_add_u32 s2, s50, 0x9b11000
	s_addc_u32 s3, s51, 0
	s_add_u32 s16, s50, s16
	v_readlane_b32 s4, v254, 59
	s_addc_u32 s17, s51, s17
	s_and_b32 s98, s4, 7
	s_lshr_b32 s99, s4, 3
	s_lshr_b32 s100, s98, 1
	s_lshl_b32 s100, s100, 2
	s_lshr_b32 s101, s99, 3
	s_add_i32 s100, s100, s101
	s_and_b32 s98, s98, 1
	s_lshl_b32 s98, s98, 3
	s_and_b32 s99, s99, 7
	s_add_i32 s98, s98, s99
	s_lshl_b32 s100, s100, 4
	s_add_i32 s98, s98, s100
	s_cmpk_eq_u32 s46, 0x100
	s_cselect_b32 s4, s98, s4
	s_lshl_b32 s0, s4, 6
	s_lshl_b32 s1, s4, 2
	s_branch .LBB0_87

.LBB0_224:
	s_lshl_b32 s0, s18, 15
	s_add_u32 s2, s20, s0
	s_addc_u32 s3, s21, 0
	s_lshr_b32 s4, s18, 7
	s_cmp_lg_u64 s[24:25], 0
	s_mov_b32 s19, s49
	s_cselect_b64 s[10:11], -1, 0
	v_readlane_b32 s15, v254, 59
	s_and_b32 s98, s15, 7
	s_lshr_b32 s99, s15, 3
	s_lshr_b32 s100, s98, 1
	s_lshl_b32 s100, s100, 2
	s_lshr_b32 s101, s99, 3
	s_add_i32 s100, s100, s101
	s_and_b32 s98, s98, 1
	s_lshl_b32 s98, s98, 3
	s_and_b32 s99, s99, 7
	s_add_i32 s98, s98, s99
	s_lshl_b32 s100, s100, 4
	s_add_i32 s98, s98, s100
	s_cmpk_eq_u32 s46, 0x100
	s_cselect_b32 s15, s98, s15
	s_lshl_b64 s[12:13], s[18:19], 1
	s_lshl_b32 s5, s15, 6
	s_lshl_b32 s14, s15, 2
	s_xor_b64 s[26:27], s[10:11], -1
	s_barrier
	s_branch .LBB0_227
